# v009 + hand-written P8 SwiGLU epilogue: g*u hoisted before the row-scale wait, act = g*u / ((1+exp2(g*c)) * (ssq/1024+eps)), widened stores
# speedup vs baseline: 1.0103x; 1.0040x over previous
.LBB0_893:
	v_lshl_add_u32 v146, s26, 8, v154
	v_ashrrev_i32_e32 v147, 31, v146
	v_lshl_add_u64 v[144:145], v[146:147], 2, s[12:13]
	global_load_dword v170, v[144:145], off
	global_load_dword v171, v[144:145], off offset:64
	global_load_dword v172, v[144:145], off offset:128
	global_load_dword v173, v[144:145], off offset:192
	global_load_dword v174, v[144:145], off offset:512
	global_load_dword v175, v[144:145], off offset:576
	global_load_dword v176, v[144:145], off offset:640
	global_load_dword v177, v[144:145], off offset:704
	v_mul_f32_e32 v125, v124, v125
	v_mul_f32_e32 v127, v126, v127
	v_mul_f32_e32 v121, v120, v121
	v_mul_f32_e32 v123, v122, v123
	v_mul_f32_e32 v117, v116, v117
	v_mul_f32_e32 v119, v118, v119
	v_mul_f32_e32 v113, v112, v113
	v_mul_f32_e32 v115, v114, v115
	v_mul_f32_e32 v109, v108, v109
	v_mul_f32_e32 v111, v110, v111
	v_mul_f32_e32 v105, v104, v105
	v_mul_f32_e32 v107, v106, v107
	v_mul_f32_e32 v101, v100, v101
	v_mul_f32_e32 v103, v102, v103
	v_mul_f32_e32 v97, v96, v97
	v_mul_f32_e32 v99, v98, v99
	v_mul_f32_e32 v93, v92, v93
	v_mul_f32_e32 v95, v94, v95
	v_mul_f32_e32 v89, v88, v89
	v_mul_f32_e32 v91, v90, v91
	v_mul_f32_e32 v85, v84, v85
	v_mul_f32_e32 v87, v86, v87
	v_mul_f32_e32 v81, v80, v81
	v_mul_f32_e32 v83, v82, v83
	v_mul_f32_e32 v77, v76, v77
	v_mul_f32_e32 v79, v78, v79
	v_mul_f32_e32 v73, v72, v73
	v_mul_f32_e32 v75, v74, v75
	v_mul_f32_e32 v69, v68, v69
	v_mul_f32_e32 v71, v70, v71
	v_mul_f32_e32 v65, v64, v65
	v_mul_f32_e32 v67, v66, v67
	v_mul_f32_e32 v61, v60, v61
	v_mul_f32_e32 v63, v62, v63
	v_mul_f32_e32 v57, v56, v57
	v_mul_f32_e32 v59, v58, v59
	v_mul_f32_e32 v53, v52, v53
	v_mul_f32_e32 v55, v54, v55
	v_mul_f32_e32 v49, v48, v49
	v_mul_f32_e32 v51, v50, v51
	v_mul_f32_e32 v45, v44, v45
	v_mul_f32_e32 v47, v46, v47
	v_mul_f32_e32 v41, v40, v41
	v_mul_f32_e32 v43, v42, v43
	v_mul_f32_e32 v37, v36, v37
	v_mul_f32_e32 v39, v38, v39
	v_mul_f32_e32 v33, v32, v33
	v_mul_f32_e32 v35, v34, v35
	v_mul_f32_e32 v29, v28, v29
	v_mul_f32_e32 v31, v30, v31
	v_mul_f32_e32 v25, v24, v25
	v_mul_f32_e32 v27, v26, v27
	v_mul_f32_e32 v21, v20, v21
	v_mul_f32_e32 v23, v22, v23
	v_mul_f32_e32 v17, v16, v17
	v_mul_f32_e32 v19, v18, v19
	v_mul_f32_e32 v13, v12, v13
	v_mul_f32_e32 v15, v14, v15
	v_mul_f32_e32 v9, v8, v9
	v_mul_f32_e32 v11, v10, v11
	v_mul_f32_e32 v5, v4, v5
	v_mul_f32_e32 v7, v6, v7
	v_mul_f32_e32 v1, v0, v1
	v_mul_f32_e32 v3, v2, v3
	s_waitcnt vmcnt(0)
	v_lshl_or_b32 v147, s55, 8, v156
	v_mov_b64_e32 v[144:145], s[10:11]
	v_mad_i64_i32 v[166:167], s[28:29], v146, s54, v[144:145]
	v_ashrrev_i32_e32 v146, 1, v147
	v_ashrrev_i32_e32 v147, 31, v146
	v_lshlrev_b64 v[146:147], 1, v[146:147]
	v_lshl_add_u64 v[166:167], v[166:167], 0, v[146:147]
	s_andn2_b64 vcc, exec, s[2:3]
	s_mov_b64 s[2:3], -1
	v_fmamk_f32 v164, v170, 0x3a800000, v160
	v_rsq_f32_e32 v162, v164
	s_nop 0
	v_mul_f32_e32 v163, 0xbfb8aa3b, v162
	v_mul_f32_e32 v144, v163, v124
	v_mul_f32_e32 v145, v163, v126
	v_mul_f32_e32 v146, v163, v120
	v_mul_f32_e32 v147, v163, v122
	v_exp_f32_e32 v144, v144
	v_exp_f32_e32 v145, v145
	v_exp_f32_e32 v146, v146
	v_exp_f32_e32 v147, v147
	v_fma_f32 v144, v144, v164, v164
	v_fma_f32 v145, v145, v164, v164
	v_fma_f32 v146, v146, v164, v164
	v_fma_f32 v147, v147, v164, v164
	v_rcp_f32_e32 v144, v144
	v_rcp_f32_e32 v145, v145
	v_rcp_f32_e32 v146, v146
	v_rcp_f32_e32 v147, v147
	v_mul_f32_e32 v148, v125, v144
	v_mul_f32_e32 v149, v127, v145
	v_mul_f32_e32 v150, v121, v146
	v_mul_f32_e32 v151, v123, v147
	v_cvt_pk_bf16_f32 v186, v148, v149
	v_cvt_pk_bf16_f32 v187, v150, v151
	v_mul_f32_e32 v178, v163, v116
	v_mul_f32_e32 v179, v163, v118
	v_mul_f32_e32 v180, v163, v112
	v_mul_f32_e32 v181, v163, v114
	v_exp_f32_e32 v178, v178
	v_exp_f32_e32 v179, v179
	v_exp_f32_e32 v180, v180
	v_exp_f32_e32 v181, v181
	v_fma_f32 v178, v178, v164, v164
	v_fma_f32 v179, v179, v164, v164
	v_fma_f32 v180, v180, v164, v164
	v_fma_f32 v181, v181, v164, v164
	v_rcp_f32_e32 v178, v178
	v_rcp_f32_e32 v179, v179
	v_rcp_f32_e32 v180, v180
	v_rcp_f32_e32 v181, v181
	v_mul_f32_e32 v182, v117, v178
	v_mul_f32_e32 v183, v119, v179
	v_mul_f32_e32 v184, v113, v180
	v_mul_f32_e32 v185, v115, v181
	v_cvt_pk_bf16_f32 v190, v182, v183
	v_cvt_pk_bf16_f32 v191, v184, v185
	v_fmamk_f32 v164, v171, 0x3a800000, v160
	v_rsq_f32_e32 v162, v164
	s_nop 0
	v_mul_f32_e32 v163, 0xbfb8aa3b, v162
	v_mul_f32_e32 v144, v163, v108
	v_mul_f32_e32 v145, v163, v110
	v_mul_f32_e32 v146, v163, v104
	v_mul_f32_e32 v147, v163, v106
	v_exp_f32_e32 v144, v144
	v_exp_f32_e32 v145, v145
	v_exp_f32_e32 v146, v146
	v_exp_f32_e32 v147, v147
	v_fma_f32 v144, v144, v164, v164
	v_fma_f32 v145, v145, v164, v164
	v_fma_f32 v146, v146, v164, v164
	v_fma_f32 v147, v147, v164, v164
	v_rcp_f32_e32 v144, v144
	v_rcp_f32_e32 v145, v145
	v_rcp_f32_e32 v146, v146
	v_rcp_f32_e32 v147, v147
	v_mul_f32_e32 v148, v109, v144
	v_mul_f32_e32 v149, v111, v145
	v_mul_f32_e32 v150, v105, v146
	v_mul_f32_e32 v151, v107, v147
	v_cvt_pk_bf16_f32 v188, v148, v149
	v_cvt_pk_bf16_f32 v189, v150, v151
	v_mul_f32_e32 v178, v163, v100
	v_mul_f32_e32 v179, v163, v102
	v_mul_f32_e32 v180, v163, v96
	v_mul_f32_e32 v181, v163, v98
	v_exp_f32_e32 v178, v178
	v_exp_f32_e32 v179, v179
	v_exp_f32_e32 v180, v180
	v_exp_f32_e32 v181, v181
	v_fma_f32 v178, v178, v164, v164
	v_fma_f32 v179, v179, v164, v164
	v_fma_f32 v180, v180, v164, v164
	v_fma_f32 v181, v181, v164, v164
	v_rcp_f32_e32 v178, v178
	v_rcp_f32_e32 v179, v179
	v_rcp_f32_e32 v180, v180
	v_rcp_f32_e32 v181, v181
	v_mul_f32_e32 v182, v101, v178
	v_mul_f32_e32 v183, v103, v179
	v_mul_f32_e32 v184, v97, v180
	v_mul_f32_e32 v185, v99, v181
	v_cvt_pk_bf16_f32 v192, v182, v183
	v_cvt_pk_bf16_f32 v193, v184, v185
	v_fmamk_f32 v164, v172, 0x3a800000, v160
	v_rsq_f32_e32 v162, v164
	s_nop 0
	v_mul_f32_e32 v163, 0xbfb8aa3b, v162
	v_mul_f32_e32 v144, v163, v92
	v_mul_f32_e32 v145, v163, v94
	v_mul_f32_e32 v146, v163, v88
	v_mul_f32_e32 v147, v163, v90
	v_exp_f32_e32 v144, v144
	v_exp_f32_e32 v145, v145
	v_exp_f32_e32 v146, v146
	v_exp_f32_e32 v147, v147
	v_fma_f32 v144, v144, v164, v164
	v_fma_f32 v145, v145, v164, v164
	v_fma_f32 v146, v146, v164, v164
	v_fma_f32 v147, v147, v164, v164
	v_rcp_f32_e32 v144, v144
	v_rcp_f32_e32 v145, v145
	v_rcp_f32_e32 v146, v146
	v_rcp_f32_e32 v147, v147
	v_mul_f32_e32 v148, v93, v144
	v_mul_f32_e32 v149, v95, v145
	v_mul_f32_e32 v150, v89, v146
	v_mul_f32_e32 v151, v91, v147
	v_cvt_pk_bf16_f32 v194, v148, v149
	v_cvt_pk_bf16_f32 v195, v150, v151
	v_mul_f32_e32 v178, v163, v84
	v_mul_f32_e32 v179, v163, v86
	v_mul_f32_e32 v180, v163, v80
	v_mul_f32_e32 v181, v163, v82
	v_exp_f32_e32 v178, v178
	v_exp_f32_e32 v179, v179
	v_exp_f32_e32 v180, v180
	v_exp_f32_e32 v181, v181
	v_fma_f32 v178, v178, v164, v164
	v_fma_f32 v179, v179, v164, v164
	v_fma_f32 v180, v180, v164, v164
	v_fma_f32 v181, v181, v164, v164
	v_rcp_f32_e32 v178, v178
	v_rcp_f32_e32 v179, v179
	v_rcp_f32_e32 v180, v180
	v_rcp_f32_e32 v181, v181
	v_mul_f32_e32 v182, v85, v178
	v_mul_f32_e32 v183, v87, v179
	v_mul_f32_e32 v184, v81, v180
	v_mul_f32_e32 v185, v83, v181
	v_cvt_pk_bf16_f32 v198, v182, v183
	v_cvt_pk_bf16_f32 v199, v184, v185
	v_fmamk_f32 v164, v173, 0x3a800000, v160
	v_rsq_f32_e32 v162, v164
	s_nop 0
	v_mul_f32_e32 v163, 0xbfb8aa3b, v162
	v_mul_f32_e32 v144, v163, v76
	v_mul_f32_e32 v145, v163, v78
	v_mul_f32_e32 v146, v163, v72
	v_mul_f32_e32 v147, v163, v74
	v_exp_f32_e32 v144, v144
	v_exp_f32_e32 v145, v145
	v_exp_f32_e32 v146, v146
	v_exp_f32_e32 v147, v147
	v_fma_f32 v144, v144, v164, v164
	v_fma_f32 v145, v145, v164, v164
	v_fma_f32 v146, v146, v164, v164
	v_fma_f32 v147, v147, v164, v164
	v_rcp_f32_e32 v144, v144
	v_rcp_f32_e32 v145, v145
	v_rcp_f32_e32 v146, v146
	v_rcp_f32_e32 v147, v147
	v_mul_f32_e32 v148, v77, v144
	v_mul_f32_e32 v149, v79, v145
	v_mul_f32_e32 v150, v73, v146
	v_mul_f32_e32 v151, v75, v147
	v_cvt_pk_bf16_f32 v196, v148, v149
	v_cvt_pk_bf16_f32 v197, v150, v151
	v_mul_f32_e32 v178, v163, v68
	v_mul_f32_e32 v179, v163, v70
	v_mul_f32_e32 v180, v163, v64
	v_mul_f32_e32 v181, v163, v66
	v_exp_f32_e32 v178, v178
	v_exp_f32_e32 v179, v179
	v_exp_f32_e32 v180, v180
	v_exp_f32_e32 v181, v181
	v_fma_f32 v178, v178, v164, v164
	v_fma_f32 v179, v179, v164, v164
	v_fma_f32 v180, v180, v164, v164
	v_fma_f32 v181, v181, v164, v164
	v_rcp_f32_e32 v178, v178
	v_rcp_f32_e32 v179, v179
	v_rcp_f32_e32 v180, v180
	v_rcp_f32_e32 v181, v181
	v_mul_f32_e32 v182, v69, v178
	v_mul_f32_e32 v183, v71, v179
	v_mul_f32_e32 v184, v65, v180
	v_mul_f32_e32 v185, v67, v181
	v_cvt_pk_bf16_f32 v200, v182, v183
	v_cvt_pk_bf16_f32 v201, v184, v185
	v_fmamk_f32 v164, v174, 0x3a800000, v160
	v_rsq_f32_e32 v162, v164
	s_nop 0
	v_mul_f32_e32 v163, 0xbfb8aa3b, v162
	v_mul_f32_e32 v144, v163, v60
	v_mul_f32_e32 v145, v163, v62
	v_mul_f32_e32 v146, v163, v56
	v_mul_f32_e32 v147, v163, v58
	v_exp_f32_e32 v144, v144
	v_exp_f32_e32 v145, v145
	v_exp_f32_e32 v146, v146
	v_exp_f32_e32 v147, v147
	v_fma_f32 v144, v144, v164, v164
	v_fma_f32 v145, v145, v164, v164
	v_fma_f32 v146, v146, v164, v164
	v_fma_f32 v147, v147, v164, v164
	v_rcp_f32_e32 v144, v144
	v_rcp_f32_e32 v145, v145
	v_rcp_f32_e32 v146, v146
	v_rcp_f32_e32 v147, v147
	v_mul_f32_e32 v148, v61, v144
	v_mul_f32_e32 v149, v63, v145
	v_mul_f32_e32 v150, v57, v146
	v_mul_f32_e32 v151, v59, v147
	v_cvt_pk_bf16_f32 v202, v148, v149
	v_cvt_pk_bf16_f32 v203, v150, v151
	v_mul_f32_e32 v178, v163, v52
	v_mul_f32_e32 v179, v163, v54
	v_mul_f32_e32 v180, v163, v48
	v_mul_f32_e32 v181, v163, v50
	v_exp_f32_e32 v178, v178
	v_exp_f32_e32 v179, v179
	v_exp_f32_e32 v180, v180
	v_exp_f32_e32 v181, v181
	v_fma_f32 v178, v178, v164, v164
	v_fma_f32 v179, v179, v164, v164
	v_fma_f32 v180, v180, v164, v164
	v_fma_f32 v181, v181, v164, v164
	v_rcp_f32_e32 v178, v178
	v_rcp_f32_e32 v179, v179
	v_rcp_f32_e32 v180, v180
	v_rcp_f32_e32 v181, v181
	v_mul_f32_e32 v182, v53, v178
	v_mul_f32_e32 v183, v55, v179
	v_mul_f32_e32 v184, v49, v180
	v_mul_f32_e32 v185, v51, v181
	v_cvt_pk_bf16_f32 v206, v182, v183
	v_cvt_pk_bf16_f32 v207, v184, v185
	v_fmamk_f32 v164, v175, 0x3a800000, v160
	v_rsq_f32_e32 v162, v164
	s_nop 0
	v_mul_f32_e32 v163, 0xbfb8aa3b, v162
	v_mul_f32_e32 v144, v163, v44
	v_mul_f32_e32 v145, v163, v46
	v_mul_f32_e32 v146, v163, v40
	v_mul_f32_e32 v147, v163, v42
	v_exp_f32_e32 v144, v144
	v_exp_f32_e32 v145, v145
	v_exp_f32_e32 v146, v146
	v_exp_f32_e32 v147, v147
	v_fma_f32 v144, v144, v164, v164
	v_fma_f32 v145, v145, v164, v164
	v_fma_f32 v146, v146, v164, v164
	v_fma_f32 v147, v147, v164, v164
	v_rcp_f32_e32 v144, v144
	v_rcp_f32_e32 v145, v145
	v_rcp_f32_e32 v146, v146
	v_rcp_f32_e32 v147, v147
	v_mul_f32_e32 v148, v45, v144
	v_mul_f32_e32 v149, v47, v145
	v_mul_f32_e32 v150, v41, v146
	v_mul_f32_e32 v151, v43, v147
	v_cvt_pk_bf16_f32 v204, v148, v149
	v_cvt_pk_bf16_f32 v205, v150, v151
	v_mul_f32_e32 v178, v163, v36
	v_mul_f32_e32 v179, v163, v38
	v_mul_f32_e32 v180, v163, v32
	v_mul_f32_e32 v181, v163, v34
	v_exp_f32_e32 v178, v178
	v_exp_f32_e32 v179, v179
	v_exp_f32_e32 v180, v180
	v_exp_f32_e32 v181, v181
	v_fma_f32 v178, v178, v164, v164
	v_fma_f32 v179, v179, v164, v164
	v_fma_f32 v180, v180, v164, v164
	v_fma_f32 v181, v181, v164, v164
	v_rcp_f32_e32 v178, v178
	v_rcp_f32_e32 v179, v179
	v_rcp_f32_e32 v180, v180
	v_rcp_f32_e32 v181, v181
	v_mul_f32_e32 v182, v37, v178
	v_mul_f32_e32 v183, v39, v179
	v_mul_f32_e32 v184, v33, v180
	v_mul_f32_e32 v185, v35, v181
	v_cvt_pk_bf16_f32 v208, v182, v183
	v_cvt_pk_bf16_f32 v209, v184, v185
	v_fmamk_f32 v164, v176, 0x3a800000, v160
	v_rsq_f32_e32 v162, v164
	s_nop 0
	v_mul_f32_e32 v163, 0xbfb8aa3b, v162
	v_mul_f32_e32 v144, v163, v28
	v_mul_f32_e32 v145, v163, v30
	v_mul_f32_e32 v146, v163, v24
	v_mul_f32_e32 v147, v163, v26
	v_exp_f32_e32 v144, v144
	v_exp_f32_e32 v145, v145
	v_exp_f32_e32 v146, v146
	v_exp_f32_e32 v147, v147
	v_fma_f32 v144, v144, v164, v164
	v_fma_f32 v145, v145, v164, v164
	v_fma_f32 v146, v146, v164, v164
	v_fma_f32 v147, v147, v164, v164
	v_rcp_f32_e32 v144, v144
	v_rcp_f32_e32 v145, v145
	v_rcp_f32_e32 v146, v146
	v_rcp_f32_e32 v147, v147
	v_mul_f32_e32 v148, v29, v144
	v_mul_f32_e32 v149, v31, v145
	v_mul_f32_e32 v150, v25, v146
	v_mul_f32_e32 v151, v27, v147
	v_cvt_pk_bf16_f32 v210, v148, v149
	v_cvt_pk_bf16_f32 v211, v150, v151
	v_mul_f32_e32 v178, v163, v20
	v_mul_f32_e32 v179, v163, v22
	v_mul_f32_e32 v180, v163, v16
	v_mul_f32_e32 v181, v163, v18
	v_exp_f32_e32 v178, v178
	v_exp_f32_e32 v179, v179
	v_exp_f32_e32 v180, v180
	v_exp_f32_e32 v181, v181
	v_fma_f32 v178, v178, v164, v164
	v_fma_f32 v179, v179, v164, v164
	v_fma_f32 v180, v180, v164, v164
	v_fma_f32 v181, v181, v164, v164
	v_rcp_f32_e32 v178, v178
	v_rcp_f32_e32 v179, v179
	v_rcp_f32_e32 v180, v180
	v_rcp_f32_e32 v181, v181
	v_mul_f32_e32 v182, v21, v178
	v_mul_f32_e32 v183, v23, v179
	v_mul_f32_e32 v184, v17, v180
	v_mul_f32_e32 v185, v19, v181
	v_cvt_pk_bf16_f32 v216, v182, v183
	v_cvt_pk_bf16_f32 v217, v184, v185
	v_fmamk_f32 v164, v177, 0x3a800000, v160
	v_rsq_f32_e32 v162, v164
	s_nop 0
	v_mul_f32_e32 v163, 0xbfb8aa3b, v162
	v_mul_f32_e32 v144, v163, v12
	v_mul_f32_e32 v145, v163, v14
	v_mul_f32_e32 v146, v163, v8
	v_mul_f32_e32 v147, v163, v10
	v_exp_f32_e32 v144, v144
	v_exp_f32_e32 v145, v145
	v_exp_f32_e32 v146, v146
	v_exp_f32_e32 v147, v147
	v_fma_f32 v144, v144, v164, v164
	v_fma_f32 v145, v145, v164, v164
	v_fma_f32 v146, v146, v164, v164
	v_fma_f32 v147, v147, v164, v164
	v_rcp_f32_e32 v144, v144
	v_rcp_f32_e32 v145, v145
	v_rcp_f32_e32 v146, v146
	v_rcp_f32_e32 v147, v147
	v_mul_f32_e32 v148, v13, v144
	v_mul_f32_e32 v149, v15, v145
	v_mul_f32_e32 v150, v9, v146
	v_mul_f32_e32 v151, v11, v147
	v_cvt_pk_bf16_f32 v212, v148, v149
	v_cvt_pk_bf16_f32 v213, v150, v151
	v_mul_f32_e32 v178, v163, v4
	v_mul_f32_e32 v179, v163, v6
	v_mul_f32_e32 v180, v163, v0
	v_mul_f32_e32 v181, v163, v2
	v_exp_f32_e32 v178, v178
	v_exp_f32_e32 v179, v179
	v_exp_f32_e32 v180, v180
	v_exp_f32_e32 v181, v181
	v_fma_f32 v178, v178, v164, v164
	v_fma_f32 v179, v179, v164, v164
	v_fma_f32 v180, v180, v164, v164
	v_fma_f32 v181, v181, v164, v164
	v_rcp_f32_e32 v178, v178
	v_rcp_f32_e32 v179, v179
	v_rcp_f32_e32 v180, v180
	v_rcp_f32_e32 v181, v181
	v_mul_f32_e32 v182, v5, v178
	v_mul_f32_e32 v183, v7, v179
	v_mul_f32_e32 v184, v1, v180
	v_mul_f32_e32 v185, v3, v181
	v_cvt_pk_bf16_f32 v218, v182, v183
	v_cvt_pk_bf16_f32 v219, v184, v185
	v_lshrrev_b32_e32 v162, 4, v214
	v_and_b32_e32 v162, 1, v162
	v_mul_u32_u24_e32 v162, 0x15ff8, v162
	v_mov_b32_e32 v163, 0
	v_lshl_add_u64 v[164:165], v[166:167], 0, v[162:163]
	s_mov_b64 s[64:65], 0x2c000
	s_mov_b64 s[66:67], 0x84000
	v_permlane16_swap_b32_e32 v186, v188
	v_permlane16_swap_b32_e32 v187, v189
	global_store_dwordx4 v[164:165], v[186:189], off
	v_permlane16_swap_b32_e32 v190, v192
	v_permlane16_swap_b32_e32 v191, v193
	global_store_dwordx4 v[164:165], v[190:193], off offset:128
	v_lshl_add_u64 v[164:165], v[164:165], 0, s[64:65]
	v_permlane16_swap_b32_e32 v194, v196
	v_permlane16_swap_b32_e32 v195, v197
	global_store_dwordx4 v[164:165], v[194:197], off
	v_permlane16_swap_b32_e32 v198, v200
	v_permlane16_swap_b32_e32 v199, v201
	global_store_dwordx4 v[164:165], v[198:201], off offset:128
	v_lshl_add_u64 v[164:165], v[164:165], 0, s[66:67]
	v_permlane16_swap_b32_e32 v202, v204
	v_permlane16_swap_b32_e32 v203, v205
	global_store_dwordx4 v[164:165], v[202:205], off
	v_permlane16_swap_b32_e32 v206, v208
	v_permlane16_swap_b32_e32 v207, v209
	global_store_dwordx4 v[164:165], v[206:209], off offset:128
	v_lshl_add_u64 v[164:165], v[164:165], 0, s[64:65]
	v_permlane16_swap_b32_e32 v210, v212
	v_permlane16_swap_b32_e32 v211, v213
	global_store_dwordx4 v[164:165], v[210:213], off
	v_permlane16_swap_b32_e32 v216, v218
	v_permlane16_swap_b32_e32 v217, v219
	global_store_dwordx4 v[164:165], v[216:219], off offset:128
	s_cbranch_vccnz .LBB0_886
	s_andn2_b64 vcc, exec, s[4:5]
	s_cbranch_vccnz .LBB0_885
	s_barrier
	s_branch .LBB0_885
